# barrier spins poll all their counters in one round trip (class + late-weights-done + memory-key owner; group + merged-done)
# baseline (speedup 1.0000x reference)
; __device__ __forceinline__ unsigned xb_ld(unsigned* p)              { return __hip_atomic_load(p, __ATOMIC_RELAXED, __HIP_MEMORY_SCOPE_AGENT); }
; __device__ __forceinline__ unsigned xb_add(unsigned* p, unsigned v) { return __hip_atomic_fetch_add(p, v, __ATOMIC_RELAXED, __HIP_MEMORY_SCOPE_AGENT); }
; #define XB_SPIN(cond, bar) do { unsigned _sp = 0; while (cond) { __builtin_amdgcn_s_sleep(1); \
;     if ((++_sp & 255u) == 0u) { if (xb_ld(&(bar)[XB_TMO])) break; if (_sp > XB_SPIN_CAP) { atomicAdd(&(bar)[XB_TMO], 1u); break; } } } } while (0)
; __device__ __forceinline__ void xcd_barrier(const XcdBarrier& b) {
;     asm volatile("s_waitcnt vmcnt(0)" ::: "memory");
;     __syncthreads();
;     if (threadIdx.x == 0) {
;         unsigned* bar = b.bar;
;         __builtin_amdgcn_s_waitcnt(0);
;         unsigned nloc = b.st[0], nx = b.st[1];
;         if (nloc == 0u) { xcd_barrier_complete(bar, b.x, nloc, nx); b.st[0] = nloc; b.st[1] = nx; }
;         const unsigned old = xb_add(&bar[XB_XSUB(b.x)], 1u);
;         const unsigned gen = old / nloc;
;         if (old + 1u == (gen + 1u) * nloc) {
;             __builtin_amdgcn_fence(__ATOMIC_RELEASE, "agent");
;             asm volatile("s_waitcnt vmcnt(0)" ::: "memory");
;             const unsigned og = xb_add(&bar[XB_TOP], 1u);
;             const unsigned tg = og / nx;
;             if (og + 1u == (tg + 1u) * nx) xb_add(&bar[XB_TOPGEN], 1u);
;             else XB_SPIN(xb_ld(&bar[XB_TOPGEN]) == tg, bar);
;             __builtin_amdgcn_fence(__ATOMIC_ACQUIRE, "agent");
;             xb_add(&bar[XB_XGEN(b.x)], 1u);
;             asm volatile("s_waitcnt vmcnt(0)" ::: "memory");
;         } else {
;             XB_SPIN(xb_ld(&bar[XB_XGEN(b.x)]) == gen, bar);
;             __builtin_amdgcn_fence(__ATOMIC_ACQUIRE, "agent");
;             asm volatile("s_waitcnt vmcnt(0)" ::: "memory");
;         }
;     }
;     __syncthreads();
; }
.Lgrpbar4_same:
	buffer_inv sc1
	global_atomic_add v1, v2, s[2:3]
	s_mov_b64 s[8:9], s[2:3]
	s_and_b32 s10, s90, 7
	s_cmp_lg_u32 s10, 0
	s_cbranch_scc1 .Lgrpbar4_mset
	s_bfe_u32 s8, s90, 0x10007
	s_lshl_b32 s8, s8, 2
	s_bfe_u32 s9, s90, 0x20003
	s_or_b32 s8, s8, s9
	s_lshl_b32 s8, s8, 7
	s_add_u32 s8, s62, s8
	s_addc_u32 s9, s63, 0
	s_add_u32 s8, s8, 0xf000
	s_addc_u32 s9, s9, 0
.Lgrpbar4_mset:
.Lgrpbar4_spin:
	global_load_dword v3, v1, s[2:3] sc1
	global_load_dword v4, v1, s[6:7] sc1
	global_load_dword v5, v1, s[8:9] sc1
	s_waitcnt vmcnt(0)
	v_cmp_lt_u32_e32 vcc, 31, v3
	s_cbranch_vccz .Lgrpbar4_retry
	v_cmp_lt_u32_e32 vcc, 0xff, v4
	s_cbranch_vccz .Lgrpbar4_retry
	v_cmp_lt_u32_e32 vcc, 31, v5
	s_cbranch_vccz .Lgrpbar4_retry
	s_branch .Lgrpbar4_done
.Lgrpbar4_retry:
	s_sleep 1
	s_add_i32 s4, s4, 1
	s_cmp_lt_u32 s4, 0x200000
	s_cbranch_scc1 .Lgrpbar4_spin

; __device__ __forceinline__ unsigned xb_ld(unsigned* p)              { return __hip_atomic_load(p, __ATOMIC_RELAXED, __HIP_MEMORY_SCOPE_AGENT); }
; #define XB_SPIN(cond, bar) do { unsigned _sp = 0; while (cond) { __builtin_amdgcn_s_sleep(1); \
;     if ((++_sp & 255u) == 0u) { if (xb_ld(&(bar)[XB_TMO])) break; if (_sp > XB_SPIN_CAP) { atomicAdd(&(bar)[XB_TMO], 1u); break; } } } } while (0)
; __device__ __forceinline__ void xcd_barrier(const XcdBarrier& b) {
;     ...
;             else XB_SPIN(xb_ld(&bar[XB_TOPGEN]) == tg, bar);
.Lgrpbar2_spin:
	global_load_dword v3, v1, s[2:3] sc1
	s_waitcnt vmcnt(0)
	v_cmp_lt_u32_e32 vcc, 7, v3
	s_cbranch_vccz .Lgrpbar2_retry
	s_branch .Lgrpbar2_done

; __device__ __forceinline__ unsigned xb_ld(unsigned* p)              { return __hip_atomic_load(p, __ATOMIC_RELAXED, __HIP_MEMORY_SCOPE_AGENT); }
; #define XB_SPIN(cond, bar) do { unsigned _sp = 0; while (cond) { __builtin_amdgcn_s_sleep(1); \
;     if ((++_sp & 255u) == 0u) { if (xb_ld(&(bar)[XB_TMO])) break; if (_sp > XB_SPIN_CAP) { atomicAdd(&(bar)[XB_TMO], 1u); break; } } } } while (0)
; __device__ __forceinline__ void xcd_barrier(const XcdBarrier& b) {
;     ...
;             else XB_SPIN(xb_ld(&bar[XB_TOPGEN]) == tg, bar);
.Lgrpbar1_spin:
	global_load_dword v3, v1, s[2:3] sc1
	global_load_dword v4, v1, s[6:7] sc1
	s_waitcnt vmcnt(0)
	v_cmp_lt_u32_e32 vcc, 7, v3
	s_cbranch_vccz .Lgrpbar1_retry
	v_cmp_lt_u32_e32 vcc, 0xff, v4
	s_cbranch_vccz .Lgrpbar1_retry
	s_branch .Lgrpbar1_done
